# adds G3+G4: mid first-half sixteen gate loads issued together and final-epilogue second-half gate loads hoisted, all with counted wait ladders
# baseline (speedup 1.0000x reference)
; __device__ __forceinline__ float bf_lo(unsigned u) { return __uint_as_float(u << 16); }
; __device__ __forceinline__ float bf_hi(unsigned u) { return __uint_as_float(u & 0xffff0000u); }
;     __device__ __forceinline__ void mid(f32x4 (&acc)[2][2][4][2], const Unit& u, int wr, int wc, int fr, int fq) const {
;     ...
;             for (int m = 0; m < 4; ++m)
; #pragma unroll
;                 for (int bj = 0; bj < 2; ++bj) { sa[m][bj] = *(const u32x4*)(sg + off + m * 16 * 2048 + bj * HALF); sb[m][bj] = *(const u32x4*)(sg + off + m * 16 * 2048 + 1024 + bj * HALF); }
; #pragma unroll
;             for (int m = 0; m < 4; ++m)
; #pragma unroll
;                 for (int bj = 0; bj < 2; ++bj) {
;                     const unsigned av[4] = {sa[m][bj].x, sa[m][bj].y, sa[m][bj].z, sa[m][bj].w}, bv[4] = {sb[m][bj].x, sb[m][bj].y, sb[m][bj].z, sb[m][bj].w};
; #pragma unroll
;                     for (int q = 0; q < 4; ++q) { const float r0 = bf_lo(av[q]) * __builtin_amdgcn_rcpf(fmaxf(bf_lo(bv[q]), 1e-30f)), r1 = bf_hi(av[q]) * __builtin_amdgcn_rcpf(fmaxf(bf_hi(bv[q]), 1e-30f));
;                         acc[ai][bj][m][q >> 1][(q & 1) * 2] *= r0; acc[ai][bj][m][q >> 1][(q & 1) * 2 + 1] *= r1; } }
.LBB0_423:
	s_cmpk_lg_i32 s26, 0x400
	s_cbranch_scc1 .LBB0_422
	v_mov_b32_e32 v194, v218
	s_nop 0
	v_lshl_add_u64 v[128:129], v[194:195], 1, s[10:11]
	global_load_dwordx4 v[184:187], v[128:129], off
	global_load_dwordx4 v[188:191], v[128:129], off offset:2048
	global_load_dwordx4 v[176:179], v[128:129], off offset:256
	global_load_dwordx4 v[180:183], v[128:129], off offset:2304
	v_add_co_u32_e32 v130, vcc, s72, v128
	v_add_u32_e32 v194, 0x40000, v194
	s_nop 0
	v_addc_co_u32_e32 v131, vcc, 0, v129, vcc
	global_load_dwordx4 v[168:171], v[130:131], off
	global_load_dwordx4 v[172:175], v[130:131], off offset:2048
	global_load_dwordx4 v[160:163], v[130:131], off offset:256
	global_load_dwordx4 v[164:167], v[130:131], off offset:2304
	v_add_co_u32_e32 v134, vcc, s43, v128
	s_nop 1
	v_addc_co_u32_e32 v135, vcc, 0, v129, vcc
	global_load_dwordx4 v[152:155], v[134:135], off
	global_load_dwordx4 v[156:159], v[134:135], off offset:2048
	global_load_dwordx4 v[144:147], v[134:135], off offset:256
	global_load_dwordx4 v[148:151], v[134:135], off offset:2304
	v_add_co_u32_e32 v132, vcc, s60, v128
	s_nop 1
	v_addc_co_u32_e32 v133, vcc, 0, v129, vcc
	global_load_dwordx4 v[136:139], v[132:133], off
	global_load_dwordx4 v[140:143], v[132:133], off offset:2048
	global_load_dwordx4 v[128:131], v[132:133], off offset:256
	s_nop 0
	global_load_dwordx4 v[132:135], v[132:133], off offset:2304
	s_waitcnt vmcnt(15)
	v_lshlrev_b32_e32 v240, 16, v184
	s_waitcnt vmcnt(14)
	v_lshlrev_b32_e32 v219, 16, v188
	v_and_b32_e32 v188, 0xffff0000, v188
	v_and_b32_e32 v241, 0xffff0000, v184
	v_lshlrev_b32_e32 v184, 16, v189
	v_max_f32_e32 v188, v188, v188
	v_max_f32_e32 v184, v184, v184
	v_max_f32_e32 v188, 0xda24260, v188
	v_max_f32_e32 v184, 0xda24260, v184
	v_rcp_f32_e32 v239, v188
	v_rcp_f32_e32 v188, v184
	v_and_b32_e32 v184, 0xffff0000, v189
	v_max_f32_e32 v184, v184, v184
	v_max_f32_e32 v184, 0xda24260, v184
	v_rcp_f32_e32 v189, v184
	v_lshlrev_b32_e32 v184, 16, v185
	v_and_b32_e32 v185, 0xffff0000, v185
	v_pk_mul_f32 v[184:185], v[188:189], v[184:185]
	v_lshlrev_b32_e32 v188, 16, v186
	v_pk_mul_f32 v[126:127], v[126:127], v[184:185]
	v_lshlrev_b32_e32 v184, 16, v190
	v_and_b32_e32 v185, 0xffff0000, v190
	v_max_f32_e32 v184, v184, v184
	v_max_f32_e32 v185, v185, v185
	v_max_f32_e32 v184, 0xda24260, v184
	v_max_f32_e32 v185, 0xda24260, v185
	v_rcp_f32_e32 v184, v184
	v_rcp_f32_e32 v185, v185
	v_and_b32_e32 v189, 0xffff0000, v186
	v_lshlrev_b32_e32 v186, 16, v187
	v_and_b32_e32 v187, 0xffff0000, v187
	v_pk_mul_f32 v[184:185], v[184:185], v[188:189]
	v_pk_mul_f32 v[120:121], v[120:121], v[184:185]
	v_lshlrev_b32_e32 v184, 16, v191
	v_and_b32_e32 v185, 0xffff0000, v191
	v_max_f32_e32 v184, v184, v184
	v_max_f32_e32 v185, v185, v185
	v_max_f32_e32 v184, 0xda24260, v184
	v_max_f32_e32 v185, 0xda24260, v185
	v_rcp_f32_e32 v184, v184
	v_rcp_f32_e32 v185, v185
	v_max_f32_e32 v219, v219, v219
	v_pk_mul_f32 v[184:185], v[184:185], v[186:187]
	s_waitcnt vmcnt(13)
	v_lshlrev_b32_e32 v186, 16, v176
	v_pk_mul_f32 v[122:123], v[122:123], v[184:185]
	s_waitcnt vmcnt(12)
	v_lshlrev_b32_e32 v184, 16, v180
	v_and_b32_e32 v180, 0xffff0000, v180
	v_and_b32_e32 v187, 0xffff0000, v176
	v_lshlrev_b32_e32 v176, 16, v181
	v_max_f32_e32 v180, v180, v180
	v_max_f32_e32 v176, v176, v176
	v_max_f32_e32 v180, 0xda24260, v180
	v_max_f32_e32 v176, 0xda24260, v176
	v_rcp_f32_e32 v185, v180
	v_rcp_f32_e32 v180, v176
	v_and_b32_e32 v176, 0xffff0000, v181
	v_max_f32_e32 v176, v176, v176
	v_max_f32_e32 v176, 0xda24260, v176
	v_rcp_f32_e32 v181, v176
	v_lshlrev_b32_e32 v176, 16, v177
	v_and_b32_e32 v177, 0xffff0000, v177
	v_pk_mul_f32 v[176:177], v[180:181], v[176:177]
	v_lshlrev_b32_e32 v180, 16, v178
	v_pk_mul_f32 v[118:119], v[118:119], v[176:177]
	v_lshlrev_b32_e32 v176, 16, v182
	v_and_b32_e32 v177, 0xffff0000, v182
	v_max_f32_e32 v176, v176, v176
	v_max_f32_e32 v177, v177, v177
	v_max_f32_e32 v176, 0xda24260, v176
	v_max_f32_e32 v177, 0xda24260, v177
	v_rcp_f32_e32 v176, v176
	v_rcp_f32_e32 v177, v177
	v_and_b32_e32 v181, 0xffff0000, v178
	v_lshlrev_b32_e32 v178, 16, v179
	v_and_b32_e32 v179, 0xffff0000, v179
	v_pk_mul_f32 v[176:177], v[176:177], v[180:181]
	v_pk_mul_f32 v[112:113], v[112:113], v[176:177]
	v_lshlrev_b32_e32 v176, 16, v183
	v_and_b32_e32 v177, 0xffff0000, v183
	v_max_f32_e32 v176, v176, v176
	v_max_f32_e32 v177, v177, v177
	v_max_f32_e32 v176, 0xda24260, v176
	v_max_f32_e32 v177, 0xda24260, v177
	v_rcp_f32_e32 v176, v176
	v_rcp_f32_e32 v177, v177
	v_max_f32_e32 v184, v184, v184
	v_max_f32_e32 v184, 0xda24260, v184
	v_pk_mul_f32 v[176:177], v[176:177], v[178:179]
	s_waitcnt vmcnt(11)
	v_lshlrev_b32_e32 v178, 16, v168
	v_pk_mul_f32 v[114:115], v[114:115], v[176:177]
	s_waitcnt vmcnt(10)
	v_lshlrev_b32_e32 v176, 16, v172
	v_and_b32_e32 v172, 0xffff0000, v172
	v_and_b32_e32 v179, 0xffff0000, v168
	v_lshlrev_b32_e32 v168, 16, v173
	v_max_f32_e32 v172, v172, v172
	v_max_f32_e32 v168, v168, v168
	v_max_f32_e32 v172, 0xda24260, v172
	v_max_f32_e32 v168, 0xda24260, v168
	v_rcp_f32_e32 v177, v172
	v_rcp_f32_e32 v172, v168
	v_and_b32_e32 v168, 0xffff0000, v173
	v_max_f32_e32 v168, v168, v168
	v_max_f32_e32 v168, 0xda24260, v168
	v_rcp_f32_e32 v173, v168
	v_lshlrev_b32_e32 v168, 16, v169
	v_and_b32_e32 v169, 0xffff0000, v169
	v_max_f32_e32 v176, v176, v176
	v_pk_mul_f32 v[168:169], v[172:173], v[168:169]
	v_lshlrev_b32_e32 v172, 16, v170
	v_pk_mul_f32 v[110:111], v[110:111], v[168:169]
	v_lshlrev_b32_e32 v168, 16, v174
	v_and_b32_e32 v169, 0xffff0000, v174
	v_max_f32_e32 v168, v168, v168
	v_max_f32_e32 v169, v169, v169
	v_max_f32_e32 v168, 0xda24260, v168
	v_max_f32_e32 v169, 0xda24260, v169
	v_rcp_f32_e32 v168, v168
	v_rcp_f32_e32 v169, v169
	v_and_b32_e32 v173, 0xffff0000, v170
	v_lshlrev_b32_e32 v170, 16, v171
	v_and_b32_e32 v171, 0xffff0000, v171
	v_pk_mul_f32 v[168:169], v[168:169], v[172:173]
	v_max_f32_e32 v176, 0xda24260, v176
	v_pk_mul_f32 v[104:105], v[104:105], v[168:169]
	v_lshlrev_b32_e32 v168, 16, v175
	v_and_b32_e32 v169, 0xffff0000, v175
	v_max_f32_e32 v168, v168, v168
	v_max_f32_e32 v169, v169, v169
	v_max_f32_e32 v168, 0xda24260, v168
	v_max_f32_e32 v169, 0xda24260, v169
	v_rcp_f32_e32 v168, v168
	v_rcp_f32_e32 v169, v169
	v_rcp_f32_e32 v176, v176
	v_rcp_f32_e32 v184, v184
	v_max_f32_e32 v219, 0xda24260, v219
	v_pk_mul_f32 v[168:169], v[168:169], v[170:171]
	s_waitcnt vmcnt(9)
; __device__ __forceinline__ float bf_lo(unsigned u) { return __uint_as_float(u << 16); }
; __device__ __forceinline__ float bf_hi(unsigned u) { return __uint_as_float(u & 0xffff0000u); }
;     __device__ __forceinline__ void mid(f32x4 (&acc)[2][2][4][2], const Unit& u, int wr, int wc, int fr, int fq) const {
;     ...
;             for (int m = 0; m < 4; ++m)
; #pragma unroll
;                 for (int bj = 0; bj < 2; ++bj) {
;                     const unsigned av[4] = {sa[m][bj].x, sa[m][bj].y, sa[m][bj].z, sa[m][bj].w}, bv[4] = {sb[m][bj].x, sb[m][bj].y, sb[m][bj].z, sb[m][bj].w};
; #pragma unroll
;                     for (int q = 0; q < 4; ++q) { const float r0 = bf_lo(av[q]) * __builtin_amdgcn_rcpf(fmaxf(bf_lo(bv[q]), 1e-30f)), r1 = bf_hi(av[q]) * __builtin_amdgcn_rcpf(fmaxf(bf_hi(bv[q]), 1e-30f));
;                         acc[ai][bj][m][q >> 1][(q & 1) * 2] *= r0; acc[ai][bj][m][q >> 1][(q & 1) * 2 + 1] *= r1; } }
	v_lshlrev_b32_e32 v170, 16, v160
	v_pk_mul_f32 v[106:107], v[106:107], v[168:169]
	s_waitcnt vmcnt(8)
	v_lshlrev_b32_e32 v168, 16, v164
	v_and_b32_e32 v164, 0xffff0000, v164
	v_and_b32_e32 v171, 0xffff0000, v160
	v_lshlrev_b32_e32 v160, 16, v165
	v_max_f32_e32 v164, v164, v164
	v_max_f32_e32 v160, v160, v160
	v_max_f32_e32 v164, 0xda24260, v164
	v_max_f32_e32 v160, 0xda24260, v160
	v_rcp_f32_e32 v169, v164
	v_rcp_f32_e32 v164, v160
	v_and_b32_e32 v160, 0xffff0000, v165
	v_max_f32_e32 v160, v160, v160
	v_max_f32_e32 v160, 0xda24260, v160
	v_rcp_f32_e32 v165, v160
	v_lshlrev_b32_e32 v160, 16, v161
	v_and_b32_e32 v161, 0xffff0000, v161
	v_pk_mul_f32 v[176:177], v[176:177], v[178:179]
	v_pk_mul_f32 v[160:161], v[164:165], v[160:161]
	v_lshlrev_b32_e32 v164, 16, v162
	v_pk_mul_f32 v[102:103], v[102:103], v[160:161]
	v_lshlrev_b32_e32 v160, 16, v166
	v_and_b32_e32 v161, 0xffff0000, v166
	v_max_f32_e32 v160, v160, v160
	v_max_f32_e32 v161, v161, v161
	v_max_f32_e32 v160, 0xda24260, v160
	v_max_f32_e32 v161, 0xda24260, v161
	v_rcp_f32_e32 v160, v160
	v_rcp_f32_e32 v161, v161
	v_and_b32_e32 v165, 0xffff0000, v162
	v_lshlrev_b32_e32 v162, 16, v163
	v_and_b32_e32 v163, 0xffff0000, v163
	v_pk_mul_f32 v[160:161], v[160:161], v[164:165]
	v_pk_mul_f32 v[108:109], v[108:109], v[176:177]
	v_pk_mul_f32 v[92:93], v[92:93], v[160:161]
	v_lshlrev_b32_e32 v160, 16, v167
	v_and_b32_e32 v161, 0xffff0000, v167
	v_max_f32_e32 v160, v160, v160
	v_max_f32_e32 v161, v161, v161
	v_max_f32_e32 v160, 0xda24260, v160
	v_max_f32_e32 v161, 0xda24260, v161
	v_rcp_f32_e32 v160, v160
	v_rcp_f32_e32 v161, v161
	v_max_f32_e32 v168, v168, v168
	v_max_f32_e32 v168, 0xda24260, v168
	v_rcp_f32_e32 v168, v168
	v_pk_mul_f32 v[160:161], v[160:161], v[162:163]
	s_waitcnt vmcnt(0)
	s_waitcnt vmcnt(0)
	v_lshlrev_b32_e32 v162, 16, v152
	v_pk_mul_f32 v[94:95], v[94:95], v[160:161]
	v_lshlrev_b32_e32 v160, 16, v156
	v_and_b32_e32 v156, 0xffff0000, v156
	v_and_b32_e32 v163, 0xffff0000, v152
	v_lshlrev_b32_e32 v152, 16, v157
	v_max_f32_e32 v156, v156, v156
	v_max_f32_e32 v152, v152, v152
	v_max_f32_e32 v156, 0xda24260, v156
	v_max_f32_e32 v152, 0xda24260, v152
	v_rcp_f32_e32 v161, v156
	v_rcp_f32_e32 v156, v152
	v_and_b32_e32 v152, 0xffff0000, v157
	v_max_f32_e32 v152, v152, v152
	v_max_f32_e32 v152, 0xda24260, v152
	v_rcp_f32_e32 v157, v152
	v_lshlrev_b32_e32 v152, 16, v153
	v_and_b32_e32 v153, 0xffff0000, v153
	v_max_f32_e32 v160, v160, v160
	v_pk_mul_f32 v[152:153], v[156:157], v[152:153]
	v_lshlrev_b32_e32 v156, 16, v154
	v_pk_mul_f32 v[98:99], v[98:99], v[152:153]
	v_lshlrev_b32_e32 v152, 16, v158
	v_and_b32_e32 v153, 0xffff0000, v158
	v_max_f32_e32 v152, v152, v152
	v_max_f32_e32 v153, v153, v153
	v_max_f32_e32 v152, 0xda24260, v152
	v_max_f32_e32 v153, 0xda24260, v153
	v_rcp_f32_e32 v152, v152
	v_rcp_f32_e32 v153, v153
	v_and_b32_e32 v157, 0xffff0000, v154
	v_lshlrev_b32_e32 v154, 16, v155
	v_and_b32_e32 v155, 0xffff0000, v155
	v_pk_mul_f32 v[152:153], v[152:153], v[156:157]
	v_max_f32_e32 v160, 0xda24260, v160
	v_pk_mul_f32 v[88:89], v[88:89], v[152:153]
	v_lshlrev_b32_e32 v152, 16, v159
	v_and_b32_e32 v153, 0xffff0000, v159
	v_max_f32_e32 v152, v152, v152
	v_max_f32_e32 v153, v153, v153
	v_max_f32_e32 v152, 0xda24260, v152
	v_max_f32_e32 v153, 0xda24260, v153
	v_rcp_f32_e32 v152, v152
	v_rcp_f32_e32 v153, v153
	v_rcp_f32_e32 v160, v160
	v_pk_mul_f32 v[184:185], v[184:185], v[186:187]
	v_pk_mul_f32 v[168:169], v[168:169], v[170:171]
	v_pk_mul_f32 v[152:153], v[152:153], v[154:155]
	v_lshlrev_b32_e32 v154, 16, v144
	v_pk_mul_f32 v[90:91], v[90:91], v[152:153]
	v_lshlrev_b32_e32 v152, 16, v148
	v_and_b32_e32 v148, 0xffff0000, v148
	v_and_b32_e32 v155, 0xffff0000, v144
	v_lshlrev_b32_e32 v144, 16, v149
	v_max_f32_e32 v148, v148, v148
	v_max_f32_e32 v144, v144, v144
	v_max_f32_e32 v148, 0xda24260, v148
	v_max_f32_e32 v144, 0xda24260, v144
	v_rcp_f32_e32 v153, v148
	v_rcp_f32_e32 v148, v144
	v_and_b32_e32 v144, 0xffff0000, v149
	v_max_f32_e32 v144, v144, v144
	v_max_f32_e32 v144, 0xda24260, v144
	v_rcp_f32_e32 v149, v144
	v_lshlrev_b32_e32 v144, 16, v145
	v_and_b32_e32 v145, 0xffff0000, v145
	v_pk_mul_f32 v[160:161], v[160:161], v[162:163]
	v_pk_mul_f32 v[144:145], v[148:149], v[144:145]
	v_lshlrev_b32_e32 v148, 16, v146
	v_pk_mul_f32 v[86:87], v[86:87], v[144:145]
	v_lshlrev_b32_e32 v144, 16, v150
	v_and_b32_e32 v145, 0xffff0000, v150
	v_max_f32_e32 v144, v144, v144
	v_max_f32_e32 v145, v145, v145
	v_max_f32_e32 v144, 0xda24260, v144
	v_max_f32_e32 v145, 0xda24260, v145
	v_rcp_f32_e32 v144, v144
	v_rcp_f32_e32 v145, v145
	v_and_b32_e32 v149, 0xffff0000, v146
	v_lshlrev_b32_e32 v146, 16, v147
	v_and_b32_e32 v147, 0xffff0000, v147
	v_pk_mul_f32 v[144:145], v[144:145], v[148:149]
	v_pk_mul_f32 v[96:97], v[96:97], v[160:161]
	v_pk_mul_f32 v[76:77], v[76:77], v[144:145]
	v_lshlrev_b32_e32 v144, 16, v151
	v_and_b32_e32 v145, 0xffff0000, v151
	v_max_f32_e32 v144, v144, v144
	v_max_f32_e32 v145, v145, v145
	v_max_f32_e32 v144, 0xda24260, v144
	v_max_f32_e32 v145, 0xda24260, v145
	v_rcp_f32_e32 v144, v144
	v_rcp_f32_e32 v145, v145
	v_pk_mul_f32 v[116:117], v[116:117], v[184:185]
	v_pk_mul_f32 v[100:101], v[100:101], v[168:169]
	v_rcp_f32_e32 v238, v219
	v_pk_mul_f32 v[144:145], v[144:145], v[146:147]
	v_lshlrev_b32_e32 v146, 16, v136
	v_pk_mul_f32 v[78:79], v[78:79], v[144:145]
	v_lshlrev_b32_e32 v144, 16, v140
	v_and_b32_e32 v140, 0xffff0000, v140
	v_and_b32_e32 v147, 0xffff0000, v136
	v_lshlrev_b32_e32 v136, 16, v141
	v_max_f32_e32 v140, v140, v140
	v_max_f32_e32 v136, v136, v136
	v_max_f32_e32 v140, 0xda24260, v140
	v_max_f32_e32 v136, 0xda24260, v136
	v_rcp_f32_e32 v145, v140
; __device__ __forceinline__ float bf_lo(unsigned u) { return __uint_as_float(u << 16); }
; __device__ __forceinline__ float bf_hi(unsigned u) { return __uint_as_float(u & 0xffff0000u); }
;     __device__ __forceinline__ void mid(f32x4 (&acc)[2][2][4][2], const Unit& u, int wr, int wc, int fr, int fq) const {
;     ...
;             for (int m = 0; m < 4; ++m)
; #pragma unroll
;                 for (int bj = 0; bj < 2; ++bj) { sa[m][bj] = *(const u32x4*)(sg + off + m * 16 * 2048 + bj * HALF); sb[m][bj] = *(const u32x4*)(sg + off + m * 16 * 2048 + 1024 + bj * HALF); }
; #pragma unroll
;             for (int m = 0; m < 4; ++m)
; #pragma unroll
;                 for (int bj = 0; bj < 2; ++bj) {
;                     const unsigned av[4] = {sa[m][bj].x, sa[m][bj].y, sa[m][bj].z, sa[m][bj].w}, bv[4] = {sb[m][bj].x, sb[m][bj].y, sb[m][bj].z, sb[m][bj].w};
; #pragma unroll
;                     for (int q = 0; q < 4; ++q) { const float r0 = bf_lo(av[q]) * __builtin_amdgcn_rcpf(fmaxf(bf_lo(bv[q]), 1e-30f)), r1 = bf_hi(av[q]) * __builtin_amdgcn_rcpf(fmaxf(bf_hi(bv[q]), 1e-30f));
;                         acc[ai][bj][m][q >> 1][(q & 1) * 2] *= r0; acc[ai][bj][m][q >> 1][(q & 1) * 2 + 1] *= r1; } }
	v_rcp_f32_e32 v140, v136
	v_and_b32_e32 v136, 0xffff0000, v141
	v_max_f32_e32 v136, v136, v136
	v_max_f32_e32 v136, 0xda24260, v136
	v_rcp_f32_e32 v141, v136
	v_lshlrev_b32_e32 v136, 16, v137
	v_and_b32_e32 v137, 0xffff0000, v137
	v_pk_mul_f32 v[238:239], v[238:239], v[240:241]
	v_pk_mul_f32 v[136:137], v[140:141], v[136:137]
	v_lshlrev_b32_e32 v140, 16, v138
	v_pk_mul_f32 v[82:83], v[82:83], v[136:137]
	v_lshlrev_b32_e32 v136, 16, v142
	v_and_b32_e32 v137, 0xffff0000, v142
	v_max_f32_e32 v136, v136, v136
	v_max_f32_e32 v137, v137, v137
	v_max_f32_e32 v136, 0xda24260, v136
	v_max_f32_e32 v137, 0xda24260, v137
	v_rcp_f32_e32 v136, v136
	v_rcp_f32_e32 v137, v137
	v_and_b32_e32 v141, 0xffff0000, v138
	v_lshlrev_b32_e32 v138, 16, v139
	v_and_b32_e32 v139, 0xffff0000, v139
	v_pk_mul_f32 v[136:137], v[136:137], v[140:141]
	v_pk_mul_f32 v[124:125], v[124:125], v[238:239]
	v_pk_mul_f32 v[72:73], v[72:73], v[136:137]
	v_lshlrev_b32_e32 v136, 16, v143
	v_and_b32_e32 v137, 0xffff0000, v143
	v_max_f32_e32 v136, v136, v136
	v_max_f32_e32 v137, v137, v137
	v_max_f32_e32 v136, 0xda24260, v136
	v_max_f32_e32 v137, 0xda24260, v137
	v_rcp_f32_e32 v136, v136
	v_rcp_f32_e32 v137, v137
	v_max_f32_e32 v152, v152, v152
	v_max_f32_e32 v144, v144, v144
	v_max_f32_e32 v152, 0xda24260, v152
	v_pk_mul_f32 v[136:137], v[136:137], v[138:139]
	v_lshlrev_b32_e32 v138, 16, v128
	v_pk_mul_f32 v[74:75], v[74:75], v[136:137]
	v_lshlrev_b32_e32 v136, 16, v132
	v_and_b32_e32 v132, 0xffff0000, v132
	v_and_b32_e32 v139, 0xffff0000, v128
	v_lshlrev_b32_e32 v128, 16, v133
	v_max_f32_e32 v132, v132, v132
	v_max_f32_e32 v128, v128, v128
	v_max_f32_e32 v132, 0xda24260, v132
	v_max_f32_e32 v128, 0xda24260, v128
	v_rcp_f32_e32 v137, v132
	v_rcp_f32_e32 v132, v128
	v_and_b32_e32 v128, 0xffff0000, v133
	v_max_f32_e32 v128, v128, v128
	v_max_f32_e32 v128, 0xda24260, v128
	v_rcp_f32_e32 v133, v128
	v_lshlrev_b32_e32 v128, 16, v129
	v_and_b32_e32 v129, 0xffff0000, v129
	v_max_f32_e32 v144, 0xda24260, v144
	v_pk_mul_f32 v[128:129], v[132:133], v[128:129]
	v_lshlrev_b32_e32 v132, 16, v130
	v_pk_mul_f32 v[70:71], v[70:71], v[128:129]
	v_lshlrev_b32_e32 v128, 16, v134
	v_and_b32_e32 v129, 0xffff0000, v134
	v_max_f32_e32 v128, v128, v128
	v_max_f32_e32 v129, v129, v129
	v_max_f32_e32 v128, 0xda24260, v128
	v_max_f32_e32 v129, 0xda24260, v129
	v_rcp_f32_e32 v128, v128
	v_rcp_f32_e32 v129, v129
	v_and_b32_e32 v133, 0xffff0000, v130
	v_lshlrev_b32_e32 v130, 16, v131
	v_and_b32_e32 v131, 0xffff0000, v131
	v_pk_mul_f32 v[128:129], v[128:129], v[132:133]
	v_rcp_f32_e32 v152, v152
	v_pk_mul_f32 v[64:65], v[64:65], v[128:129]
	v_lshlrev_b32_e32 v128, 16, v135
	v_and_b32_e32 v129, 0xffff0000, v135
	v_max_f32_e32 v128, v128, v128
	v_max_f32_e32 v129, v129, v129
	v_max_f32_e32 v128, 0xda24260, v128
	v_max_f32_e32 v129, 0xda24260, v129
	v_rcp_f32_e32 v128, v128
	v_rcp_f32_e32 v129, v129
	v_rcp_f32_e32 v144, v144
	v_pk_mul_f32 v[152:153], v[152:153], v[154:155]
	v_max_f32_e32 v136, v136, v136
	v_pk_mul_f32 v[128:129], v[128:129], v[130:131]
	v_pk_mul_f32 v[144:145], v[144:145], v[146:147]
	v_pk_mul_f32 v[66:67], v[66:67], v[128:129]
	v_lshl_add_u64 v[128:129], v[194:195], 1, s[10:11]
	global_load_dwordx4 v[172:175], v[128:129], off
	global_load_dwordx4 v[176:179], v[128:129], off offset:2048
	global_load_dwordx4 v[160:163], v[128:129], off offset:256
	global_load_dwordx4 v[188:191], v[128:129], off offset:2304
	v_add_co_u32_e32 v130, vcc, s72, v128
	v_pk_mul_f32 v[84:85], v[84:85], v[152:153]
	s_nop 0
	v_addc_co_u32_e32 v131, vcc, 0, v129, vcc
	global_load_dwordx4 v[180:183], v[130:131], off
	global_load_dwordx4 v[184:187], v[130:131], off offset:2048
	global_load_dwordx4 v[164:167], v[130:131], off offset:256
	global_load_dwordx4 v[168:171], v[130:131], off offset:2304
	v_add_co_u32_e32 v130, vcc, s43, v128
	v_pk_mul_f32 v[80:81], v[80:81], v[144:145]
	s_nop 0
	v_addc_co_u32_e32 v131, vcc, 0, v129, vcc
	global_load_dwordx4 v[152:155], v[130:131], off
	global_load_dwordx4 v[156:159], v[130:131], off offset:2048
	global_load_dwordx4 v[144:147], v[130:131], off offset:256
	global_load_dwordx4 v[148:151], v[130:131], off offset:2304
	v_max_f32_e32 v136, 0xda24260, v136
	v_rcp_f32_e32 v136, v136
	v_add_co_u32_e32 v132, vcc, s60, v128
	v_pk_mul_f32 v[136:137], v[136:137], v[138:139]
	s_nop 0
	v_addc_co_u32_e32 v133, vcc, 0, v129, vcc
	v_pk_mul_f32 v[68:69], v[68:69], v[136:137]
	global_load_dwordx4 v[136:139], v[132:133], off
	global_load_dwordx4 v[140:143], v[132:133], off offset:2048
	global_load_dwordx4 v[128:131], v[132:133], off offset:256
	s_nop 0
	global_load_dwordx4 v[132:135], v[132:133], off offset:2304
	s_waitcnt vmcnt(15)
	v_lshlrev_b32_e32 v240, 16, v172
	s_waitcnt vmcnt(14)
	v_lshlrev_b32_e32 v194, 16, v176
	v_and_b32_e32 v176, 0xffff0000, v176
	v_and_b32_e32 v241, 0xffff0000, v172
	v_lshlrev_b32_e32 v172, 16, v177
	v_max_f32_e32 v176, v176, v176
	v_max_f32_e32 v172, v172, v172
	v_max_f32_e32 v176, 0xda24260, v176
	v_max_f32_e32 v172, 0xda24260, v172
	v_rcp_f32_e32 v239, v176
	v_rcp_f32_e32 v176, v172
	v_and_b32_e32 v172, 0xffff0000, v177
	v_max_f32_e32 v172, v172, v172
	v_max_f32_e32 v172, 0xda24260, v172
	v_rcp_f32_e32 v177, v172
	v_lshlrev_b32_e32 v172, 16, v173
	v_and_b32_e32 v173, 0xffff0000, v173
	v_max_f32_e32 v194, v194, v194
	v_pk_mul_f32 v[172:173], v[176:177], v[172:173]
	v_lshlrev_b32_e32 v176, 16, v174
	v_pk_mul_f32 v[62:63], v[62:63], v[172:173]
	v_lshlrev_b32_e32 v172, 16, v178
	v_and_b32_e32 v173, 0xffff0000, v178
	v_max_f32_e32 v172, v172, v172
	v_max_f32_e32 v173, v173, v173
	v_max_f32_e32 v172, 0xda24260, v172
	v_max_f32_e32 v173, 0xda24260, v173
	v_rcp_f32_e32 v172, v172
	v_rcp_f32_e32 v173, v173
	v_and_b32_e32 v177, 0xffff0000, v174
	v_lshlrev_b32_e32 v174, 16, v175
	v_and_b32_e32 v175, 0xffff0000, v175
	v_pk_mul_f32 v[172:173], v[172:173], v[176:177]
	v_max_f32_e32 v194, 0xda24260, v194
	v_pk_mul_f32 v[56:57], v[56:57], v[172:173]
	v_lshlrev_b32_e32 v172, 16, v179
	v_and_b32_e32 v173, 0xffff0000, v179
	v_max_f32_e32 v172, v172, v172
	v_max_f32_e32 v173, v173, v173
	v_max_f32_e32 v172, 0xda24260, v172
	v_max_f32_e32 v173, 0xda24260, v173
	v_rcp_f32_e32 v172, v172
	v_rcp_f32_e32 v173, v173
	v_rcp_f32_e32 v238, v194
	v_pk_mul_f32 v[172:173], v[172:173], v[174:175]
	s_nop 0
	v_pk_mul_f32 v[58:59], v[58:59], v[172:173]
	s_waitcnt vmcnt(12)
; __device__ __forceinline__ float bf_lo(unsigned u) { return __uint_as_float(u << 16); }
; __device__ __forceinline__ float bf_hi(unsigned u) { return __uint_as_float(u & 0xffff0000u); }
;     __device__ __forceinline__ void mid(f32x4 (&acc)[2][2][4][2], const Unit& u, int wr, int wc, int fr, int fq) const {
;     ...
;             for (int m = 0; m < 4; ++m)
; #pragma unroll
;                 for (int bj = 0; bj < 2; ++bj) {
;                     const unsigned av[4] = {sa[m][bj].x, sa[m][bj].y, sa[m][bj].z, sa[m][bj].w}, bv[4] = {sb[m][bj].x, sb[m][bj].y, sb[m][bj].z, sb[m][bj].w};
; #pragma unroll
;                     for (int q = 0; q < 4; ++q) { const float r0 = bf_lo(av[q]) * __builtin_amdgcn_rcpf(fmaxf(bf_lo(bv[q]), 1e-30f)), r1 = bf_hi(av[q]) * __builtin_amdgcn_rcpf(fmaxf(bf_hi(bv[q]), 1e-30f));
;                         acc[ai][bj][m][q >> 1][(q & 1) * 2] *= r0; acc[ai][bj][m][q >> 1][(q & 1) * 2 + 1] *= r1; } }
	v_lshlrev_b32_e32 v172, 16, v188
	v_and_b32_e32 v173, 0xffff0000, v188
	v_max_f32_e32 v172, v172, v172
	v_max_f32_e32 v173, v173, v173
	v_max_f32_e32 v172, 0xda24260, v172
	v_max_f32_e32 v173, 0xda24260, v173
	v_rcp_f32_e32 v172, v172
	v_rcp_f32_e32 v173, v173
	v_lshlrev_b32_e32 v174, 16, v160
	v_and_b32_e32 v175, 0xffff0000, v160
	v_lshlrev_b32_e32 v160, 16, v189
	v_max_f32_e32 v160, v160, v160
	v_pk_mul_f32 v[172:173], v[172:173], v[174:175]
	v_max_f32_e32 v160, 0xda24260, v160
	v_pk_mul_f32 v[52:53], v[52:53], v[172:173]
	v_rcp_f32_e32 v172, v160
	v_and_b32_e32 v160, 0xffff0000, v189
	v_max_f32_e32 v160, v160, v160
	v_max_f32_e32 v160, 0xda24260, v160
	v_rcp_f32_e32 v173, v160
	v_lshlrev_b32_e32 v160, 16, v161
	v_and_b32_e32 v161, 0xffff0000, v161
	v_pk_mul_f32 v[238:239], v[238:239], v[240:241]
	v_pk_mul_f32 v[160:161], v[172:173], v[160:161]
	v_lshlrev_b32_e32 v172, 16, v162
	v_pk_mul_f32 v[54:55], v[54:55], v[160:161]
	v_lshlrev_b32_e32 v160, 16, v190
	v_and_b32_e32 v161, 0xffff0000, v190
	v_max_f32_e32 v160, v160, v160
	v_max_f32_e32 v161, v161, v161
	v_max_f32_e32 v160, 0xda24260, v160
	v_max_f32_e32 v161, 0xda24260, v161
	v_rcp_f32_e32 v160, v160
	v_rcp_f32_e32 v161, v161
	v_and_b32_e32 v173, 0xffff0000, v162
	v_lshlrev_b32_e32 v162, 16, v163
	v_and_b32_e32 v163, 0xffff0000, v163
	v_pk_mul_f32 v[160:161], v[160:161], v[172:173]
	v_pk_mul_f32 v[60:61], v[60:61], v[238:239]
	v_pk_mul_f32 v[44:45], v[44:45], v[160:161]
	v_lshlrev_b32_e32 v160, 16, v191
	v_and_b32_e32 v161, 0xffff0000, v191
	v_max_f32_e32 v160, v160, v160
	v_max_f32_e32 v161, v161, v161
	v_max_f32_e32 v160, 0xda24260, v160
	v_max_f32_e32 v161, 0xda24260, v161
	v_rcp_f32_e32 v160, v160
	v_rcp_f32_e32 v161, v161
	s_nop 0
	v_pk_mul_f32 v[160:161], v[160:161], v[162:163]
	s_nop 0
	v_pk_mul_f32 v[46:47], v[46:47], v[160:161]
	s_waitcnt vmcnt(10)
	v_lshlrev_b32_e32 v160, 16, v184
	v_and_b32_e32 v161, 0xffff0000, v184
	v_max_f32_e32 v160, v160, v160
	v_max_f32_e32 v161, v161, v161
	v_max_f32_e32 v160, 0xda24260, v160
	v_max_f32_e32 v161, 0xda24260, v161
	v_rcp_f32_e32 v160, v160
	v_rcp_f32_e32 v161, v161
	v_lshlrev_b32_e32 v162, 16, v180
	v_and_b32_e32 v163, 0xffff0000, v180
	v_pk_mul_f32 v[160:161], v[160:161], v[162:163]
	s_nop 0
	v_pk_mul_f32 v[48:49], v[48:49], v[160:161]
	v_lshlrev_b32_e32 v160, 16, v185
	v_and_b32_e32 v161, 0xffff0000, v185
	v_max_f32_e32 v160, v160, v160
	v_max_f32_e32 v161, v161, v161
	v_max_f32_e32 v160, 0xda24260, v160
	v_max_f32_e32 v161, 0xda24260, v161
	v_rcp_f32_e32 v160, v160
	v_rcp_f32_e32 v161, v161
	v_lshlrev_b32_e32 v162, 16, v181
	v_and_b32_e32 v163, 0xffff0000, v181
	v_pk_mul_f32 v[160:161], v[160:161], v[162:163]
	s_nop 0
	v_pk_mul_f32 v[50:51], v[50:51], v[160:161]
	v_lshlrev_b32_e32 v160, 16, v186
	v_and_b32_e32 v161, 0xffff0000, v186
	v_max_f32_e32 v160, v160, v160
	v_max_f32_e32 v161, v161, v161
	v_max_f32_e32 v160, 0xda24260, v160
	v_max_f32_e32 v161, 0xda24260, v161
	v_rcp_f32_e32 v160, v160
	v_rcp_f32_e32 v161, v161
	v_lshlrev_b32_e32 v162, 16, v182
	v_and_b32_e32 v163, 0xffff0000, v182
	v_pk_mul_f32 v[160:161], v[160:161], v[162:163]
	s_nop 0
	v_pk_mul_f32 v[40:41], v[40:41], v[160:161]
	v_lshlrev_b32_e32 v160, 16, v187
	v_and_b32_e32 v161, 0xffff0000, v187
	v_max_f32_e32 v160, v160, v160
	v_max_f32_e32 v161, v161, v161
	v_max_f32_e32 v160, 0xda24260, v160
	v_max_f32_e32 v161, 0xda24260, v161
	v_rcp_f32_e32 v160, v160
	v_rcp_f32_e32 v161, v161
	v_lshlrev_b32_e32 v162, 16, v183
	v_and_b32_e32 v163, 0xffff0000, v183
	v_pk_mul_f32 v[160:161], v[160:161], v[162:163]
	s_nop 0
	v_pk_mul_f32 v[42:43], v[42:43], v[160:161]
	s_waitcnt vmcnt(8)
	v_lshlrev_b32_e32 v160, 16, v168
	v_and_b32_e32 v161, 0xffff0000, v168
	v_max_f32_e32 v160, v160, v160
	v_max_f32_e32 v161, v161, v161
	v_max_f32_e32 v160, 0xda24260, v160
	v_max_f32_e32 v161, 0xda24260, v161
	v_rcp_f32_e32 v160, v160
	v_rcp_f32_e32 v161, v161
	v_lshlrev_b32_e32 v162, 16, v164
	v_and_b32_e32 v163, 0xffff0000, v164
	v_pk_mul_f32 v[160:161], v[160:161], v[162:163]
	s_nop 0
	v_pk_mul_f32 v[36:37], v[36:37], v[160:161]
	v_lshlrev_b32_e32 v160, 16, v169
	v_and_b32_e32 v161, 0xffff0000, v169
	v_max_f32_e32 v160, v160, v160
	v_max_f32_e32 v161, v161, v161
	v_max_f32_e32 v160, 0xda24260, v160
	v_max_f32_e32 v161, 0xda24260, v161
	v_rcp_f32_e32 v160, v160
	v_rcp_f32_e32 v161, v161
	v_lshlrev_b32_e32 v162, 16, v165
	v_and_b32_e32 v163, 0xffff0000, v165
	v_pk_mul_f32 v[160:161], v[160:161], v[162:163]
	s_nop 0
	v_pk_mul_f32 v[38:39], v[38:39], v[160:161]
	v_lshlrev_b32_e32 v160, 16, v170
	v_and_b32_e32 v161, 0xffff0000, v170
	v_max_f32_e32 v160, v160, v160
	v_max_f32_e32 v161, v161, v161
	v_max_f32_e32 v160, 0xda24260, v160
	v_max_f32_e32 v161, 0xda24260, v161
	v_rcp_f32_e32 v160, v160
	v_rcp_f32_e32 v161, v161
	v_lshlrev_b32_e32 v162, 16, v166
	v_and_b32_e32 v163, 0xffff0000, v166
	v_pk_mul_f32 v[160:161], v[160:161], v[162:163]
	s_nop 0
	v_pk_mul_f32 v[28:29], v[28:29], v[160:161]
	v_lshlrev_b32_e32 v160, 16, v171
	v_and_b32_e32 v161, 0xffff0000, v171
	v_max_f32_e32 v160, v160, v160
	v_max_f32_e32 v161, v161, v161
	v_max_f32_e32 v160, 0xda24260, v160
	v_max_f32_e32 v161, 0xda24260, v161
	v_rcp_f32_e32 v160, v160
	v_rcp_f32_e32 v161, v161
	v_lshlrev_b32_e32 v162, 16, v167
	v_and_b32_e32 v163, 0xffff0000, v167
	v_pk_mul_f32 v[160:161], v[160:161], v[162:163]
	s_nop 0
	v_pk_mul_f32 v[30:31], v[30:31], v[160:161]
	s_waitcnt vmcnt(6)
; __device__ __forceinline__ float bf_lo(unsigned u) { return __uint_as_float(u << 16); }
; __device__ __forceinline__ float bf_hi(unsigned u) { return __uint_as_float(u & 0xffff0000u); }
;     __device__ __forceinline__ void mid(f32x4 (&acc)[2][2][4][2], const Unit& u, int wr, int wc, int fr, int fq) const {
;     ...
;             for (int m = 0; m < 4; ++m)
; #pragma unroll
;                 for (int bj = 0; bj < 2; ++bj) {
;                     const unsigned av[4] = {sa[m][bj].x, sa[m][bj].y, sa[m][bj].z, sa[m][bj].w}, bv[4] = {sb[m][bj].x, sb[m][bj].y, sb[m][bj].z, sb[m][bj].w};
; #pragma unroll
;                     for (int q = 0; q < 4; ++q) { const float r0 = bf_lo(av[q]) * __builtin_amdgcn_rcpf(fmaxf(bf_lo(bv[q]), 1e-30f)), r1 = bf_hi(av[q]) * __builtin_amdgcn_rcpf(fmaxf(bf_hi(bv[q]), 1e-30f));
;                         acc[ai][bj][m][q >> 1][(q & 1) * 2] *= r0; acc[ai][bj][m][q >> 1][(q & 1) * 2 + 1] *= r1; } }
	v_lshlrev_b32_e32 v160, 16, v156
	v_and_b32_e32 v156, 0xffff0000, v156
	v_lshlrev_b32_e32 v162, 16, v152
	v_and_b32_e32 v163, 0xffff0000, v152
	v_lshlrev_b32_e32 v152, 16, v157
	v_max_f32_e32 v156, v156, v156
	v_max_f32_e32 v152, v152, v152
	v_max_f32_e32 v156, 0xda24260, v156
	v_max_f32_e32 v152, 0xda24260, v152
	v_rcp_f32_e32 v161, v156
	v_rcp_f32_e32 v156, v152
	v_and_b32_e32 v152, 0xffff0000, v157
	v_max_f32_e32 v152, v152, v152
	v_max_f32_e32 v152, 0xda24260, v152
	v_rcp_f32_e32 v157, v152
	v_lshlrev_b32_e32 v152, 16, v153
	v_and_b32_e32 v153, 0xffff0000, v153
	v_max_f32_e32 v160, v160, v160
	v_pk_mul_f32 v[152:153], v[156:157], v[152:153]
	v_lshlrev_b32_e32 v156, 16, v154
	v_pk_mul_f32 v[34:35], v[34:35], v[152:153]
	v_lshlrev_b32_e32 v152, 16, v158
	v_and_b32_e32 v153, 0xffff0000, v158
	v_max_f32_e32 v152, v152, v152
	v_max_f32_e32 v153, v153, v153
	v_max_f32_e32 v152, 0xda24260, v152
	v_max_f32_e32 v153, 0xda24260, v153
	v_rcp_f32_e32 v152, v152
	v_rcp_f32_e32 v153, v153
	v_and_b32_e32 v157, 0xffff0000, v154
	v_lshlrev_b32_e32 v154, 16, v155
	v_and_b32_e32 v155, 0xffff0000, v155
	v_pk_mul_f32 v[152:153], v[152:153], v[156:157]
	v_max_f32_e32 v160, 0xda24260, v160
	v_pk_mul_f32 v[24:25], v[24:25], v[152:153]
	v_lshlrev_b32_e32 v152, 16, v159
	v_and_b32_e32 v153, 0xffff0000, v159
	v_max_f32_e32 v152, v152, v152
	v_max_f32_e32 v153, v153, v153
	v_max_f32_e32 v152, 0xda24260, v152
	v_max_f32_e32 v153, 0xda24260, v153
	v_rcp_f32_e32 v152, v152
	v_rcp_f32_e32 v153, v153
	v_rcp_f32_e32 v160, v160
	v_pk_mul_f32 v[152:153], v[152:153], v[154:155]
	s_nop 0
	v_pk_mul_f32 v[26:27], v[26:27], v[152:153]
	s_waitcnt vmcnt(4)
	v_lshlrev_b32_e32 v152, 16, v148
	v_and_b32_e32 v148, 0xffff0000, v148
	v_lshlrev_b32_e32 v154, 16, v144
	v_and_b32_e32 v155, 0xffff0000, v144
	v_lshlrev_b32_e32 v144, 16, v149
	v_max_f32_e32 v148, v148, v148
	v_max_f32_e32 v144, v144, v144
	v_max_f32_e32 v148, 0xda24260, v148
	v_max_f32_e32 v144, 0xda24260, v144
	v_rcp_f32_e32 v153, v148
	v_rcp_f32_e32 v148, v144
	v_and_b32_e32 v144, 0xffff0000, v149
	v_max_f32_e32 v144, v144, v144
	v_max_f32_e32 v144, 0xda24260, v144
	v_rcp_f32_e32 v149, v144
	v_lshlrev_b32_e32 v144, 16, v145
	v_and_b32_e32 v145, 0xffff0000, v145
	v_max_f32_e32 v152, v152, v152
	v_pk_mul_f32 v[144:145], v[148:149], v[144:145]
	v_lshlrev_b32_e32 v148, 16, v146
	v_pk_mul_f32 v[22:23], v[22:23], v[144:145]
	v_lshlrev_b32_e32 v144, 16, v150
	v_and_b32_e32 v145, 0xffff0000, v150
	v_max_f32_e32 v144, v144, v144
	v_max_f32_e32 v145, v145, v145
	v_max_f32_e32 v144, 0xda24260, v144
	v_max_f32_e32 v145, 0xda24260, v145
	v_rcp_f32_e32 v144, v144
	v_rcp_f32_e32 v145, v145
	v_and_b32_e32 v149, 0xffff0000, v146
	v_lshlrev_b32_e32 v146, 16, v147
	v_and_b32_e32 v147, 0xffff0000, v147
	v_pk_mul_f32 v[144:145], v[144:145], v[148:149]
	v_max_f32_e32 v152, 0xda24260, v152
	v_pk_mul_f32 v[12:13], v[12:13], v[144:145]
	v_lshlrev_b32_e32 v144, 16, v151
	v_and_b32_e32 v145, 0xffff0000, v151
	v_max_f32_e32 v144, v144, v144
	v_max_f32_e32 v145, v145, v145
	v_max_f32_e32 v144, 0xda24260, v144
	v_max_f32_e32 v145, 0xda24260, v145
	v_rcp_f32_e32 v144, v144
	v_rcp_f32_e32 v145, v145
	v_rcp_f32_e32 v152, v152
	v_pk_mul_f32 v[160:161], v[160:161], v[162:163]
	v_pk_mul_f32 v[144:145], v[144:145], v[146:147]
	s_nop 0
	v_pk_mul_f32 v[14:15], v[14:15], v[144:145]
	s_waitcnt vmcnt(2)
	v_lshlrev_b32_e32 v144, 16, v140
	v_and_b32_e32 v140, 0xffff0000, v140
	v_lshlrev_b32_e32 v146, 16, v136
	v_and_b32_e32 v147, 0xffff0000, v136
	v_lshlrev_b32_e32 v136, 16, v141
	v_max_f32_e32 v140, v140, v140
	v_max_f32_e32 v136, v136, v136
	v_max_f32_e32 v140, 0xda24260, v140
	v_max_f32_e32 v136, 0xda24260, v136
	v_rcp_f32_e32 v145, v140
	v_rcp_f32_e32 v140, v136
	v_and_b32_e32 v136, 0xffff0000, v141
	v_max_f32_e32 v136, v136, v136
	v_max_f32_e32 v136, 0xda24260, v136
	v_rcp_f32_e32 v141, v136
	v_lshlrev_b32_e32 v136, 16, v137
	v_and_b32_e32 v137, 0xffff0000, v137
	v_max_f32_e32 v144, v144, v144
	v_pk_mul_f32 v[136:137], v[140:141], v[136:137]
	v_lshlrev_b32_e32 v140, 16, v138
	v_pk_mul_f32 v[18:19], v[18:19], v[136:137]
	v_lshlrev_b32_e32 v136, 16, v142
	v_and_b32_e32 v137, 0xffff0000, v142
	v_max_f32_e32 v136, v136, v136
	v_max_f32_e32 v137, v137, v137
	v_max_f32_e32 v136, 0xda24260, v136
	v_max_f32_e32 v137, 0xda24260, v137
	v_rcp_f32_e32 v136, v136
	v_rcp_f32_e32 v137, v137
	v_and_b32_e32 v141, 0xffff0000, v138
	v_lshlrev_b32_e32 v138, 16, v139
	v_and_b32_e32 v139, 0xffff0000, v139
	v_pk_mul_f32 v[136:137], v[136:137], v[140:141]
	v_max_f32_e32 v144, 0xda24260, v144
	v_pk_mul_f32 v[8:9], v[8:9], v[136:137]
	v_lshlrev_b32_e32 v136, 16, v143
	v_and_b32_e32 v137, 0xffff0000, v143
	v_max_f32_e32 v136, v136, v136
	v_max_f32_e32 v137, v137, v137
	v_max_f32_e32 v136, 0xda24260, v136
	v_max_f32_e32 v137, 0xda24260, v137
	v_rcp_f32_e32 v136, v136
	v_rcp_f32_e32 v137, v137
	v_rcp_f32_e32 v144, v144
	v_pk_mul_f32 v[152:153], v[152:153], v[154:155]
	v_pk_mul_f32 v[32:33], v[32:33], v[160:161]
	v_pk_mul_f32 v[136:137], v[136:137], v[138:139]
	s_waitcnt vmcnt(1)
	v_lshlrev_b32_e32 v138, 16, v128
	v_pk_mul_f32 v[10:11], v[10:11], v[136:137]
	s_waitcnt vmcnt(0)
	v_lshlrev_b32_e32 v136, 16, v132
	v_and_b32_e32 v132, 0xffff0000, v132
	v_and_b32_e32 v139, 0xffff0000, v128
	v_lshlrev_b32_e32 v128, 16, v133
	v_max_f32_e32 v132, v132, v132
	v_max_f32_e32 v128, v128, v128
	v_max_f32_e32 v132, 0xda24260, v132
	v_max_f32_e32 v128, 0xda24260, v128
	v_rcp_f32_e32 v137, v132
	v_rcp_f32_e32 v132, v128
	v_and_b32_e32 v128, 0xffff0000, v133
	v_max_f32_e32 v128, v128, v128
	v_max_f32_e32 v128, 0xda24260, v128
	v_rcp_f32_e32 v133, v128
	v_lshlrev_b32_e32 v128, 16, v129
	v_and_b32_e32 v129, 0xffff0000, v129
	v_max_f32_e32 v136, v136, v136
	v_pk_mul_f32 v[128:129], v[132:133], v[128:129]
	v_lshlrev_b32_e32 v132, 16, v130
	v_pk_mul_f32 v[6:7], v[6:7], v[128:129]
	v_lshlrev_b32_e32 v128, 16, v134
	v_and_b32_e32 v129, 0xffff0000, v134
	v_max_f32_e32 v128, v128, v128
	v_max_f32_e32 v129, v129, v129
	v_max_f32_e32 v128, 0xda24260, v128
	v_max_f32_e32 v129, 0xda24260, v129
	v_rcp_f32_e32 v128, v128
	v_rcp_f32_e32 v129, v129
	v_and_b32_e32 v133, 0xffff0000, v130
	v_max_f32_e32 v136, 0xda24260, v136
	v_rcp_f32_e32 v136, v136
	v_pk_mul_f32 v[128:129], v[128:129], v[132:133]
	v_lshlrev_b32_e32 v130, 16, v131
	v_pk_mul_f32 v[0:1], v[0:1], v[128:129]
	v_lshlrev_b32_e32 v128, 16, v135
	v_and_b32_e32 v129, 0xffff0000, v135
	v_max_f32_e32 v128, v128, v128
	v_max_f32_e32 v129, v129, v129
	v_max_f32_e32 v128, 0xda24260, v128
	v_max_f32_e32 v129, 0xda24260, v129
	v_rcp_f32_e32 v128, v128
	v_rcp_f32_e32 v129, v129
	v_and_b32_e32 v131, 0xffff0000, v131
	v_pk_mul_f32 v[144:145], v[144:145], v[146:147]
	v_pk_mul_f32 v[136:137], v[136:137], v[138:139]
	v_pk_mul_f32 v[128:129], v[128:129], v[130:131]
	v_pk_mul_f32 v[20:21], v[20:21], v[152:153]
	v_pk_mul_f32 v[16:17], v[16:17], v[144:145]
	v_pk_mul_f32 v[4:5], v[4:5], v[136:137]
	v_pk_mul_f32 v[2:3], v[2:3], v[128:129]
	s_branch .LBB0_422

; __device__ __forceinline__ unsigned cvt_pk_bf16(float lo, float hi) { unsigned r; asm volatile("v_cvt_pk_bf16_f32 %0, %1, %2" : "=v"(r) : "v"(lo), "v"(hi)); return r; }
; __device__ __forceinline__ float bf_lo(unsigned u) { return __uint_as_float(u << 16); }
; __device__ __forceinline__ float bf_hi(unsigned u) { return __uint_as_float(u & 0xffff0000u); }
;     __device__ __forceinline__ void operator()(const f32x4 (&acc)[2][2][4][2], const Unit& u, int wr, int wc, int fr, int fq) const {
;     ...
;             for (int m = 0; m < 4; ++m)
; #pragma unroll
;                 for (int bj = 0; bj < 2; ++bj) sb[m][bj] = *(const u32x4*)(sg + off + m * 16 * 2048 + 1024 + bj * HALF);
;             const unsigned mo = (off >> 11) * 1024u + (off & 2047u);
; #pragma unroll
;             for (int m = 0; m < 4; ++m)
; #pragma unroll
;                 for (int bj = 0; bj < 2; ++bj) { const u32x4 s = sb[m][bj];
;                     const f32x4 a0 = acc[ai][bj][m][0], a1 = acc[ai][bj][m][1];
;                     u32x4 w; w.x = cvt_pk_bf16(a0[0] * bf_lo(s.x), a0[1] * bf_hi(s.x)); w.y = cvt_pk_bf16(a0[2] * bf_lo(s.y), a0[3] * bf_hi(s.y));
;                     w.z = cvt_pk_bf16(a1[0] * bf_lo(s.z), a1[1] * bf_hi(s.z)); w.w = cvt_pk_bf16(a1[2] * bf_lo(s.w), a1[3] * bf_hi(s.w));
;                     *(u32x4*)(merged + mo + m * 16 * 1024 + bj * HALF) = w; }
.LBB0_427:
	v_mov_b32_e32 v219, v195
	s_mov_b32 s1, 0x8000
	v_lshl_add_u64 v[128:129], v[218:219], 1, s[10:11]
	global_load_dwordx4 v[156:159], v[128:129], off offset:2048
	global_load_dwordx4 v[152:155], v[128:129], off offset:2304
	v_add_co_u32_e32 v130, vcc, 0x10000, v128
	v_lshrrev_b32_e32 v160, 1, v218
	s_nop 0
	v_addc_co_u32_e32 v131, vcc, 0, v129, vcc
	global_load_dwordx4 v[148:151], v[130:131], off offset:2048
	global_load_dwordx4 v[144:147], v[130:131], off offset:2304
	v_add_co_u32_e32 v130, vcc, 0x20000, v128
	v_and_b32_e32 v160, 0x7ffffc00, v160
	s_nop 0
	v_addc_co_u32_e32 v131, vcc, 0, v129, vcc
	global_load_dwordx4 v[140:143], v[130:131], off offset:2048
	global_load_dwordx4 v[136:139], v[130:131], off offset:2304
	v_add_co_u32_e32 v128, vcc, 0x30000, v128
	v_and_b32_e32 v161, 0x7ff, v218
	s_nop 0
	v_addc_co_u32_e32 v129, vcc, 0, v129, vcc
	global_load_dwordx4 v[132:135], v[128:129], off offset:2048
	s_nop 0
	global_load_dwordx4 v[128:131], v[128:129], off offset:2304
	v_add_u32_e32 v194, v160, v161
	v_add_u32_e32 v190, 0x40000, v218
	v_mov_b32_e32 v191, 0
	v_lshl_add_u64 v[184:185], v[190:191], 1, s[10:11]
	global_load_dwordx4 v[160:163], v[184:185], off offset:2048
	global_load_dwordx4 v[164:167], v[184:185], off offset:2304
	v_add_co_u32_e32 v172, vcc, s72, v184
	s_nop 1
	v_addc_co_u32_e32 v173, vcc, 0, v185, vcc
	global_load_dwordx4 v[168:171], v[172:173], off offset:2048
	s_nop 0
	global_load_dwordx4 v[172:175], v[172:173], off offset:2304
	v_add_co_u32_e32 v180, vcc, s43, v184
	s_nop 1
	v_addc_co_u32_e32 v181, vcc, 0, v185, vcc
	global_load_dwordx4 v[176:179], v[180:181], off offset:2048
	s_nop 0
	global_load_dwordx4 v[180:183], v[180:181], off offset:2304
	v_add_co_u32_e32 v188, vcc, s60, v184
	s_nop 1
	v_addc_co_u32_e32 v189, vcc, 0, v185, vcc
	global_load_dwordx4 v[184:187], v[188:189], off offset:2048
	s_nop 0
	global_load_dwordx4 v[188:191], v[188:189], off offset:2304
	s_mov_b32 s0, 0x18000
	s_waitcnt vmcnt(15)
	v_lshlrev_b32_e32 v219, 16, v156
	v_and_b32_e32 v156, 0xffff0000, v156
	v_mul_f32_e32 v124, v124, v219
	v_mul_f32_e32 v125, v125, v156
	v_cvt_pk_bf16_f32 v124, v124, v125
	v_lshlrev_b32_e32 v125, 16, v157
	v_mul_f32_e32 v125, v126, v125
	v_and_b32_e32 v126, 0xffff0000, v157
	v_mul_f32_e32 v126, v127, v126
	v_cvt_pk_bf16_f32 v125, v125, v126
	v_lshlrev_b32_e32 v126, 16, v158
	v_mul_f32_e32 v120, v120, v126
	v_and_b32_e32 v126, 0xffff0000, v158
	v_mul_f32_e32 v121, v121, v126
	v_cvt_pk_bf16_f32 v126, v120, v121
	v_lshlrev_b32_e32 v120, 16, v159
	v_mul_f32_e32 v120, v122, v120
	v_and_b32_e32 v121, 0xffff0000, v159
	s_waitcnt vmcnt(14)
	v_lshlrev_b32_e32 v122, 16, v152
	v_mul_f32_e32 v121, v123, v121
	v_mul_f32_e32 v116, v116, v122
	v_and_b32_e32 v122, 0xffff0000, v152
	v_cvt_pk_bf16_f32 v127, v120, v121
	v_lshl_add_u64 v[120:121], v[194:195], 1, s[12:13]
	v_mul_f32_e32 v117, v117, v122
	global_store_dwordx4 v[120:121], v[124:127], off
	v_cvt_pk_bf16_f32 v116, v116, v117
	v_lshlrev_b32_e32 v117, 16, v153
	v_mul_f32_e32 v117, v118, v117
	v_and_b32_e32 v118, 0xffff0000, v153
	v_mul_f32_e32 v118, v119, v118
	v_cvt_pk_bf16_f32 v117, v117, v118
	v_lshlrev_b32_e32 v118, 16, v154
	v_mul_f32_e32 v112, v112, v118
	v_and_b32_e32 v118, 0xffff0000, v154
	v_mul_f32_e32 v113, v113, v118
	v_cvt_pk_bf16_f32 v118, v112, v113
	v_lshlrev_b32_e32 v112, 16, v155
	v_mul_f32_e32 v112, v114, v112
	v_and_b32_e32 v113, 0xffff0000, v155
	v_mul_f32_e32 v113, v115, v113
	v_cvt_pk_bf16_f32 v119, v112, v113
	s_waitcnt vmcnt(14)
	v_lshlrev_b32_e32 v112, 16, v148
	v_mul_f32_e32 v108, v108, v112
	v_and_b32_e32 v112, 0xffff0000, v148
	v_mul_f32_e32 v109, v109, v112
	global_store_dwordx4 v[120:121], v[116:119], off offset:256
	v_cvt_pk_bf16_f32 v108, v108, v109
	v_lshlrev_b32_e32 v109, 16, v149
	v_mul_f32_e32 v109, v110, v109
	v_and_b32_e32 v110, 0xffff0000, v149
	v_mul_f32_e32 v110, v111, v110
	v_cvt_pk_bf16_f32 v109, v109, v110
	v_lshlrev_b32_e32 v110, 16, v150
	v_mul_f32_e32 v104, v104, v110
	v_and_b32_e32 v110, 0xffff0000, v150
	v_mul_f32_e32 v105, v105, v110
	v_cvt_pk_bf16_f32 v110, v104, v105
	v_lshlrev_b32_e32 v104, 16, v151
	v_mul_f32_e32 v104, v106, v104
	v_and_b32_e32 v105, 0xffff0000, v151
	s_waitcnt vmcnt(14)
	v_lshlrev_b32_e32 v106, 16, v144
	v_mul_f32_e32 v105, v107, v105
	v_cvt_pk_bf16_f32 v111, v104, v105
	v_add_co_u32_e32 v104, vcc, s1, v120
	v_mul_f32_e32 v100, v100, v106
	v_and_b32_e32 v106, 0xffff0000, v144
	v_addc_co_u32_e32 v105, vcc, 0, v121, vcc
	v_mul_f32_e32 v101, v101, v106
	global_store_dwordx4 v[104:105], v[108:111], off
	v_cvt_pk_bf16_f32 v100, v100, v101
	v_lshlrev_b32_e32 v101, 16, v145
	v_mul_f32_e32 v101, v102, v101
	v_and_b32_e32 v102, 0xffff0000, v145
	v_mul_f32_e32 v102, v103, v102
	v_cvt_pk_bf16_f32 v101, v101, v102
	v_lshlrev_b32_e32 v102, 16, v146
	v_mul_f32_e32 v92, v92, v102
	v_and_b32_e32 v102, 0xffff0000, v146
	v_mul_f32_e32 v93, v93, v102
	v_cvt_pk_bf16_f32 v102, v92, v93
	v_lshlrev_b32_e32 v92, 16, v147
	v_and_b32_e32 v93, 0xffff0000, v147
	v_mul_f32_e32 v92, v94, v92
	v_mul_f32_e32 v93, v95, v93
	v_cvt_pk_bf16_f32 v103, v92, v93
	s_waitcnt vmcnt(14)
	v_lshlrev_b32_e32 v92, 16, v140
	v_and_b32_e32 v93, 0xffff0000, v140
	v_mul_f32_e32 v92, v96, v92
	v_mul_f32_e32 v93, v97, v93
	global_store_dwordx4 v[104:105], v[100:103], off offset:256
	v_cvt_pk_bf16_f32 v92, v92, v93
	v_lshlrev_b32_e32 v93, 16, v141
	v_and_b32_e32 v94, 0xffff0000, v141
	v_mul_f32_e32 v93, v98, v93
	v_mul_f32_e32 v94, v99, v94
	v_cvt_pk_bf16_f32 v93, v93, v94
	v_lshlrev_b32_e32 v94, 16, v142
	v_mul_f32_e32 v88, v88, v94
	v_and_b32_e32 v94, 0xffff0000, v142
	v_mul_f32_e32 v89, v89, v94
	v_cvt_pk_bf16_f32 v94, v88, v89
	v_lshlrev_b32_e32 v88, 16, v143
	v_mul_f32_e32 v88, v90, v88
	v_and_b32_e32 v89, 0xffff0000, v143
	s_waitcnt vmcnt(14)
; __device__ __forceinline__ unsigned cvt_pk_bf16(float lo, float hi) { unsigned r; asm volatile("v_cvt_pk_bf16_f32 %0, %1, %2" : "=v"(r) : "v"(lo), "v"(hi)); return r; }
; __device__ __forceinline__ float bf_lo(unsigned u) { return __uint_as_float(u << 16); }
; __device__ __forceinline__ float bf_hi(unsigned u) { return __uint_as_float(u & 0xffff0000u); }
;     __device__ __forceinline__ void operator()(const f32x4 (&acc)[2][2][4][2], const Unit& u, int wr, int wc, int fr, int fq) const {
;     ...
;             for (int m = 0; m < 4; ++m)
; #pragma unroll
;                 for (int bj = 0; bj < 2; ++bj) sb[m][bj] = *(const u32x4*)(sg + off + m * 16 * 2048 + 1024 + bj * HALF);
;             const unsigned mo = (off >> 11) * 1024u + (off & 2047u);
; #pragma unroll
;             for (int m = 0; m < 4; ++m)
; #pragma unroll
;                 for (int bj = 0; bj < 2; ++bj) { const u32x4 s = sb[m][bj];
;                     const f32x4 a0 = acc[ai][bj][m][0], a1 = acc[ai][bj][m][1];
;                     u32x4 w; w.x = cvt_pk_bf16(a0[0] * bf_lo(s.x), a0[1] * bf_hi(s.x)); w.y = cvt_pk_bf16(a0[2] * bf_lo(s.y), a0[3] * bf_hi(s.y));
;                     w.z = cvt_pk_bf16(a1[0] * bf_lo(s.z), a1[1] * bf_hi(s.z)); w.w = cvt_pk_bf16(a1[2] * bf_lo(s.w), a1[3] * bf_hi(s.w));
;                     *(u32x4*)(merged + mo + m * 16 * 1024 + bj * HALF) = w; }
;             off += 128u * 2048u; }
	v_lshlrev_b32_e32 v90, 16, v136
	v_mul_f32_e32 v89, v91, v89
	v_cvt_pk_bf16_f32 v95, v88, v89
	v_add_co_u32_e32 v88, vcc, s72, v120
	v_mul_f32_e32 v84, v84, v90
	v_and_b32_e32 v90, 0xffff0000, v136
	v_addc_co_u32_e32 v89, vcc, 0, v121, vcc
	v_mul_f32_e32 v85, v85, v90
	global_store_dwordx4 v[88:89], v[92:95], off
	v_cvt_pk_bf16_f32 v84, v84, v85
	v_lshlrev_b32_e32 v85, 16, v137
	v_mul_f32_e32 v85, v86, v85
	v_and_b32_e32 v86, 0xffff0000, v137
	v_mul_f32_e32 v86, v87, v86
	v_cvt_pk_bf16_f32 v85, v85, v86
	v_lshlrev_b32_e32 v86, 16, v138
	v_mul_f32_e32 v76, v76, v86
	v_and_b32_e32 v86, 0xffff0000, v138
	v_mul_f32_e32 v77, v77, v86
	v_cvt_pk_bf16_f32 v86, v76, v77
	v_lshlrev_b32_e32 v76, 16, v139
	v_and_b32_e32 v77, 0xffff0000, v139
	v_mul_f32_e32 v76, v78, v76
	v_mul_f32_e32 v77, v79, v77
	v_cvt_pk_bf16_f32 v87, v76, v77
	s_waitcnt vmcnt(14)
	v_lshlrev_b32_e32 v76, 16, v132
	v_and_b32_e32 v77, 0xffff0000, v132
	v_mul_f32_e32 v76, v80, v76
	v_mul_f32_e32 v77, v81, v77
	global_store_dwordx4 v[88:89], v[84:87], off offset:256
	v_cvt_pk_bf16_f32 v76, v76, v77
	v_lshlrev_b32_e32 v77, 16, v133
	v_and_b32_e32 v78, 0xffff0000, v133
	v_mul_f32_e32 v77, v82, v77
	v_mul_f32_e32 v78, v83, v78
	v_cvt_pk_bf16_f32 v77, v77, v78
	v_lshlrev_b32_e32 v78, 16, v134
	v_mul_f32_e32 v72, v72, v78
	v_and_b32_e32 v78, 0xffff0000, v134
	v_mul_f32_e32 v73, v73, v78
	v_cvt_pk_bf16_f32 v78, v72, v73
	v_lshlrev_b32_e32 v72, 16, v135
	v_mul_f32_e32 v72, v74, v72
	v_and_b32_e32 v73, 0xffff0000, v135
	s_waitcnt vmcnt(14)
	v_lshlrev_b32_e32 v74, 16, v128
	v_mul_f32_e32 v73, v75, v73
	v_cvt_pk_bf16_f32 v79, v72, v73
	v_add_co_u32_e32 v72, vcc, s0, v120
	v_mul_f32_e32 v68, v68, v74
	v_and_b32_e32 v74, 0xffff0000, v128
	v_addc_co_u32_e32 v73, vcc, 0, v121, vcc
	v_mul_f32_e32 v69, v69, v74
	global_store_dwordx4 v[72:73], v[76:79], off
	v_cvt_pk_bf16_f32 v68, v68, v69
	v_lshlrev_b32_e32 v69, 16, v129
	v_mul_f32_e32 v69, v70, v69
	v_and_b32_e32 v70, 0xffff0000, v129
	v_mul_f32_e32 v70, v71, v70
	v_cvt_pk_bf16_f32 v69, v69, v70
	v_lshlrev_b32_e32 v70, 16, v130
	v_mul_f32_e32 v64, v64, v70
	v_and_b32_e32 v70, 0xffff0000, v130
	v_mul_f32_e32 v65, v65, v70
	v_cvt_pk_bf16_f32 v70, v64, v65
	v_lshlrev_b32_e32 v64, 16, v131
	v_and_b32_e32 v65, 0xffff0000, v131
	v_mul_f32_e32 v64, v66, v64
	v_mul_f32_e32 v65, v67, v65
	v_cvt_pk_bf16_f32 v71, v64, v65
	global_store_dwordx4 v[72:73], v[68:71], off offset:256
	v_add_u32_e32 v194, 0x40000, v218
	v_lshrrev_b32_e32 v96, 1, v194
	v_and_b32_e32 v96, 0x7ffffc00, v96
	v_and_b32_e32 v97, 0x7ff, v194
	v_add_u32_e32 v194, v96, v97
	s_waitcnt vmcnt(8)
	s_waitcnt vmcnt(15)
	v_lshlrev_b32_e32 v96, 16, v160
	v_and_b32_e32 v160, 0xffff0000, v160
	v_mul_f32_e32 v60, v60, v96
	v_mul_f32_e32 v61, v61, v160
	v_cvt_pk_bf16_f32 v60, v60, v61
	v_lshlrev_b32_e32 v61, 16, v161
	v_mul_f32_e32 v61, v62, v61
	v_and_b32_e32 v62, 0xffff0000, v161
	v_mul_f32_e32 v62, v63, v62
	v_cvt_pk_bf16_f32 v61, v61, v62
	v_lshlrev_b32_e32 v62, 16, v162
	v_mul_f32_e32 v56, v56, v62
	v_and_b32_e32 v62, 0xffff0000, v162
	v_mul_f32_e32 v57, v57, v62
	v_cvt_pk_bf16_f32 v62, v56, v57
	v_lshlrev_b32_e32 v56, 16, v163
	v_mul_f32_e32 v56, v58, v56
	v_and_b32_e32 v57, 0xffff0000, v163
	s_waitcnt vmcnt(14)
	v_lshlrev_b32_e32 v58, 16, v164
	v_mul_f32_e32 v57, v59, v57
	v_mul_f32_e32 v52, v52, v58
	v_and_b32_e32 v58, 0xffff0000, v164
	v_cvt_pk_bf16_f32 v63, v56, v57
	v_lshl_add_u64 v[56:57], v[194:195], 1, s[12:13]
	v_mul_f32_e32 v53, v53, v58
	global_store_dwordx4 v[56:57], v[60:63], off
	v_cvt_pk_bf16_f32 v52, v52, v53
	v_lshlrev_b32_e32 v53, 16, v165
	v_mul_f32_e32 v53, v54, v53
	v_and_b32_e32 v54, 0xffff0000, v165
	v_mul_f32_e32 v54, v55, v54
	v_cvt_pk_bf16_f32 v53, v53, v54
	v_lshlrev_b32_e32 v54, 16, v166
	v_mul_f32_e32 v44, v44, v54
	v_and_b32_e32 v54, 0xffff0000, v166
	v_mul_f32_e32 v45, v45, v54
	v_cvt_pk_bf16_f32 v54, v44, v45
	v_lshlrev_b32_e32 v44, 16, v167
	v_and_b32_e32 v45, 0xffff0000, v167
	v_mul_f32_e32 v44, v46, v44
	v_mul_f32_e32 v45, v47, v45
	v_cvt_pk_bf16_f32 v55, v44, v45
	s_waitcnt vmcnt(14)
; __device__ __forceinline__ unsigned cvt_pk_bf16(float lo, float hi) { unsigned r; asm volatile("v_cvt_pk_bf16_f32 %0, %1, %2" : "=v"(r) : "v"(lo), "v"(hi)); return r; }
; __device__ __forceinline__ float bf_lo(unsigned u) { return __uint_as_float(u << 16); }
; __device__ __forceinline__ float bf_hi(unsigned u) { return __uint_as_float(u & 0xffff0000u); }
;     __device__ __forceinline__ void operator()(const f32x4 (&acc)[2][2][4][2], const Unit& u, int wr, int wc, int fr, int fq) const {
;     ...
;             for (int m = 0; m < 4; ++m)
; #pragma unroll
;                 for (int bj = 0; bj < 2; ++bj) { const u32x4 s = sb[m][bj];
;                     const f32x4 a0 = acc[ai][bj][m][0], a1 = acc[ai][bj][m][1];
;                     u32x4 w; w.x = cvt_pk_bf16(a0[0] * bf_lo(s.x), a0[1] * bf_hi(s.x)); w.y = cvt_pk_bf16(a0[2] * bf_lo(s.y), a0[3] * bf_hi(s.y));
;                     w.z = cvt_pk_bf16(a1[0] * bf_lo(s.z), a1[1] * bf_hi(s.z)); w.w = cvt_pk_bf16(a1[2] * bf_lo(s.w), a1[3] * bf_hi(s.w));
;                     *(u32x4*)(merged + mo + m * 16 * 1024 + bj * HALF) = w; }
	v_lshlrev_b32_e32 v44, 16, v168
	v_and_b32_e32 v45, 0xffff0000, v168
	v_mul_f32_e32 v44, v48, v44
	v_mul_f32_e32 v45, v49, v45
	global_store_dwordx4 v[56:57], v[52:55], off offset:256
	v_cvt_pk_bf16_f32 v44, v44, v45
	v_lshlrev_b32_e32 v45, 16, v169
	v_and_b32_e32 v46, 0xffff0000, v169
	v_mul_f32_e32 v45, v50, v45
	v_mul_f32_e32 v46, v51, v46
	v_cvt_pk_bf16_f32 v45, v45, v46
	v_lshlrev_b32_e32 v46, 16, v170
	v_mul_f32_e32 v40, v40, v46
	v_and_b32_e32 v46, 0xffff0000, v170
	v_mul_f32_e32 v41, v41, v46
	v_cvt_pk_bf16_f32 v46, v40, v41
	v_lshlrev_b32_e32 v40, 16, v171
	v_mul_f32_e32 v40, v42, v40
	v_and_b32_e32 v41, 0xffff0000, v171
	s_waitcnt vmcnt(14)
	v_lshlrev_b32_e32 v42, 16, v172
	v_mul_f32_e32 v41, v43, v41
	v_cvt_pk_bf16_f32 v47, v40, v41
	v_add_co_u32_e32 v40, vcc, s1, v56
	v_mul_f32_e32 v36, v36, v42
	v_and_b32_e32 v42, 0xffff0000, v172
	v_addc_co_u32_e32 v41, vcc, 0, v57, vcc
	v_mul_f32_e32 v37, v37, v42
	global_store_dwordx4 v[40:41], v[44:47], off
	v_cvt_pk_bf16_f32 v36, v36, v37
	v_lshlrev_b32_e32 v37, 16, v173
	v_mul_f32_e32 v37, v38, v37
	v_and_b32_e32 v38, 0xffff0000, v173
	v_mul_f32_e32 v38, v39, v38
	v_cvt_pk_bf16_f32 v37, v37, v38
	v_lshlrev_b32_e32 v38, 16, v174
	v_mul_f32_e32 v28, v28, v38
	v_and_b32_e32 v38, 0xffff0000, v174
	v_mul_f32_e32 v29, v29, v38
	v_cvt_pk_bf16_f32 v38, v28, v29
	v_lshlrev_b32_e32 v28, 16, v175
	v_and_b32_e32 v29, 0xffff0000, v175
	v_mul_f32_e32 v28, v30, v28
	v_mul_f32_e32 v29, v31, v29
	v_cvt_pk_bf16_f32 v39, v28, v29
	s_waitcnt vmcnt(14)
	v_lshlrev_b32_e32 v28, 16, v176
	v_and_b32_e32 v29, 0xffff0000, v176
	v_mul_f32_e32 v28, v32, v28
	v_mul_f32_e32 v29, v33, v29
	global_store_dwordx4 v[40:41], v[36:39], off offset:256
	v_cvt_pk_bf16_f32 v28, v28, v29
	v_lshlrev_b32_e32 v29, 16, v177
	v_and_b32_e32 v30, 0xffff0000, v177
	v_mul_f32_e32 v29, v34, v29
	v_mul_f32_e32 v30, v35, v30
	v_cvt_pk_bf16_f32 v29, v29, v30
	v_lshlrev_b32_e32 v30, 16, v178
	v_mul_f32_e32 v24, v24, v30
	v_and_b32_e32 v30, 0xffff0000, v178
	v_mul_f32_e32 v25, v25, v30
	v_cvt_pk_bf16_f32 v30, v24, v25
	v_lshlrev_b32_e32 v24, 16, v179
	v_mul_f32_e32 v24, v26, v24
	v_and_b32_e32 v25, 0xffff0000, v179
	s_waitcnt vmcnt(14)
	v_lshlrev_b32_e32 v26, 16, v180
	v_mul_f32_e32 v25, v27, v25
	v_cvt_pk_bf16_f32 v31, v24, v25
	v_add_co_u32_e32 v24, vcc, s72, v56
	v_mul_f32_e32 v20, v20, v26
	v_and_b32_e32 v26, 0xffff0000, v180
	v_addc_co_u32_e32 v25, vcc, 0, v57, vcc
	v_mul_f32_e32 v21, v21, v26
	global_store_dwordx4 v[24:25], v[28:31], off
	v_cvt_pk_bf16_f32 v20, v20, v21
	v_lshlrev_b32_e32 v21, 16, v181
	v_mul_f32_e32 v21, v22, v21
	v_and_b32_e32 v22, 0xffff0000, v181
	v_mul_f32_e32 v22, v23, v22
	v_cvt_pk_bf16_f32 v21, v21, v22
	v_lshlrev_b32_e32 v22, 16, v182
	v_mul_f32_e32 v12, v12, v22
	v_and_b32_e32 v22, 0xffff0000, v182
	v_mul_f32_e32 v13, v13, v22
	v_cvt_pk_bf16_f32 v22, v12, v13
	v_lshlrev_b32_e32 v12, 16, v183
	v_and_b32_e32 v13, 0xffff0000, v183
	v_mul_f32_e32 v12, v14, v12
	v_mul_f32_e32 v13, v15, v13
	v_cvt_pk_bf16_f32 v23, v12, v13
	s_waitcnt vmcnt(14)
	v_lshlrev_b32_e32 v12, 16, v184
	v_and_b32_e32 v13, 0xffff0000, v184
	v_mul_f32_e32 v12, v16, v12
	v_mul_f32_e32 v13, v17, v13
	global_store_dwordx4 v[24:25], v[20:23], off offset:256
	v_cvt_pk_bf16_f32 v12, v12, v13
	v_lshlrev_b32_e32 v13, 16, v185
	v_and_b32_e32 v14, 0xffff0000, v185
	v_mul_f32_e32 v13, v18, v13
	v_mul_f32_e32 v14, v19, v14
	v_cvt_pk_bf16_f32 v13, v13, v14
	v_lshlrev_b32_e32 v14, 16, v186
	v_mul_f32_e32 v8, v8, v14
	v_and_b32_e32 v14, 0xffff0000, v186
	v_mul_f32_e32 v9, v9, v14
	v_cvt_pk_bf16_f32 v14, v8, v9
	v_lshlrev_b32_e32 v8, 16, v187
	v_mul_f32_e32 v8, v10, v8
	v_and_b32_e32 v9, 0xffff0000, v187
	s_waitcnt vmcnt(14)
	v_lshlrev_b32_e32 v10, 16, v188
	v_mul_f32_e32 v9, v11, v9
	v_cvt_pk_bf16_f32 v15, v8, v9
	v_add_co_u32_e32 v8, vcc, s0, v56
	v_mul_f32_e32 v4, v4, v10
	v_and_b32_e32 v10, 0xffff0000, v188
	v_addc_co_u32_e32 v9, vcc, 0, v57, vcc
	v_mul_f32_e32 v5, v5, v10
	global_store_dwordx4 v[8:9], v[12:15], off
	v_cvt_pk_bf16_f32 v4, v4, v5
	v_lshlrev_b32_e32 v5, 16, v189
	v_mul_f32_e32 v5, v6, v5
	v_and_b32_e32 v6, 0xffff0000, v189
	v_mul_f32_e32 v6, v7, v6
	v_cvt_pk_bf16_f32 v5, v5, v6
	v_lshlrev_b32_e32 v6, 16, v190
	v_mul_f32_e32 v0, v0, v6
	v_and_b32_e32 v6, 0xffff0000, v190
	v_mul_f32_e32 v1, v1, v6
	v_cvt_pk_bf16_f32 v6, v0, v1
	v_lshlrev_b32_e32 v0, 16, v191
	v_and_b32_e32 v1, 0xffff0000, v191
	s_mov_b64 s[0:1], -1
	s_andn2_b64 vcc, exec, s[6:7]
	v_mul_f32_e32 v0, v2, v0
	v_mul_f32_e32 v1, v3, v1
	v_cvt_pk_bf16_f32 v7, v0, v1
	global_store_dwordx4 v[8:9], v[4:7], off offset:256
	s_cbranch_vccnz .LBB0_414
	s_andn2_b64 vcc, exec, s[8:9]
	s_cbranch_vccnz .LBB0_413
	s_barrier
	s_branch .LBB0_413
